# P3 Toeplitz fill of Wy hand-written: four items per pass, masked table loads issued together and waited once
# speedup vs baseline: 1.0221x; 1.0029x over previous
; DI unsigned pack2bf(float a, float b) { const f2_t v = {a, b}; return __builtin_bit_cast(unsigned, __builtin_convertvector(v, bf2_t)); }
; DI void phase3(const Params& P, char* smem) {
;     ...
;     for (long idx = (long)tvb * 256 + VT; idx < 32L * 1024 * 128; idx += (long)tnvb * 256) {
;       int g = (int)(idx >> 17), n = (int)(idx >> 7) & 1023, k8 = (int)idx & 127, i = n >> 4, h = n & 15, j = k8 >> 1, hp0 = (k8 & 1) * 8;
;       if (k8 * 8 >= ((n >> 7) + 1) * 128) continue;
;       uint4 o = make_uint4(0, 0, 0, 0);
;       if (j <= i) {
;         const float4* kp = reinterpret_cast<const float4*>(Ktab + ((g * 64 + (i - j)) * 16 + h) * 16 + hp0);
;         float4 a = kp[0], b = kp[1];
;         o = make_uint4(pack2bf(a.x, a.y), pack2bf(a.z, a.w), pack2bf(b.x, b.y), pack2bf(b.z, b.w));
;       }
;       *reinterpret_cast<uint4*>(Wy + ((long)g * 1024 + n) * UGLD + k8 * 8) = o;
;     }
.LBB0_690:
	s_and_b64 vcc, exec, s[0:1]
	s_cbranch_vccz .LBB0_699
	s_mov_b64 s[0:1], 0x400000
	v_cmp_gt_i64_e32 vcc, s[0:1], v[4:5]
	s_and_saveexec_b64 s[0:1], vcc
	s_cbranch_execz .LBB0_698
	s_lshl_b32 s2, s2, 1
	s_sub_i32 s6, s2, 32
	s_and_b64 s[4:5], exec, s[4:5]
	v_and_b32_e32 v0, 0x7f, v189
	v_mov_b32_e32 v6, 0
	s_cselect_b32 s6, s6, s2
	v_lshlrev_b32_e32 v15, 3, v0
	v_lshlrev_b32_e32 v0, 4, v0
	v_mov_b32_e32 v1, v6
	s_ashr_i32 s7, s6, 31
	v_lshl_add_u64 v[0:1], s[78:79], 0, v[0:1]
	s_mov_b64 s[8:9], 0x10400000
	s_lshl_b64 s[4:5], s[6:7], 8
	v_bfe_u32 v14, v189, 1, 6
	v_lshl_add_u64 v[8:9], v[0:1], 0, s[8:9]
	v_lshlrev_b64 v[10:11], 3, v[4:5]
	s_lshl_b64 s[6:7], s[6:7], 11
	s_mov_b64 s[8:9], 0
	s_movk_i32 s2, 0x900
	s_mov_b64 s[10:11], 0x3fffff
	v_and_b32_e32 v250, 1, v189
	v_lshlrev_b32_e32 v250, 5, v250
	v_mov_b32_e32 v251, 0
	s_mov_b64 s[22:23], exec
.Lp3_toep_loop:
	v_cmp_ge_i64_e64 s[32:33], s[10:11], v[4:5]
	v_lshrrev_b32_e32 v7, 7, v4
	v_and_b32_e32 v0, 0x380, v7
	v_add_u32_e32 v0, 0x80, v0
	v_cmp_lt_u32_e64 s[26:27], v15, v0
	v_lshrrev_b32_e32 v12, 17, v4
	v_bfe_u32 v13, v7, 4, 6
	s_and_b64 s[32:33], s[32:33], s[26:27]
	v_cmp_ge_u32_e64 s[26:27], v13, v14
	v_sub_u32_e32 v1, v13, v14
	v_and_b32_e32 v0, 15, v7
	v_lshlrev_b32_e32 v3, 10, v12
	s_and_b64 s[40:41], s[32:33], s[26:27]
	v_lshlrev_b32_e32 v1, 4, v1
	v_or3_b32 v0, v1, v3, v0
	v_lshlrev_b32_e32 v0, 4, v0
	v_ashrrev_i32_e32 v1, 31, v0
	v_lshl_add_u64 v[0:1], v[0:1], 2, s[16:17]
	v_lshl_add_u64 v[0:1], v[0:1], 0, v[250:251]
	v_and_b32_e32 v16, 0x3ff, v7
	v_lshl_or_b32 v16, v12, 10, v16
	v_mad_u64_u32 v[242:243], s[26:27], v16, s2, v[8:9]
	v_mov_b64_e32 v[210:211], 0
	v_mov_b64_e32 v[212:213], 0
	v_mov_b64_e32 v[214:215], 0
	v_mov_b64_e32 v[216:217], 0
	s_mov_b64 exec, s[40:41]
	global_load_dwordx4 v[210:213], v[0:1], off
	global_load_dwordx4 v[214:217], v[0:1], off offset:16
	s_mov_b64 exec, s[22:23]
	v_lshl_add_u64 v[4:5], v[4:5], 0, s[4:5]
	v_cmp_ge_i64_e64 s[34:35], s[10:11], v[4:5]
	v_lshrrev_b32_e32 v7, 7, v4
	v_and_b32_e32 v0, 0x380, v7
	v_add_u32_e32 v0, 0x80, v0
	v_cmp_lt_u32_e64 s[26:27], v15, v0
	v_lshrrev_b32_e32 v12, 17, v4
	v_bfe_u32 v13, v7, 4, 6
	s_and_b64 s[34:35], s[34:35], s[26:27]
	v_cmp_ge_u32_e64 s[26:27], v13, v14
	v_sub_u32_e32 v1, v13, v14
	v_and_b32_e32 v0, 15, v7
	v_lshlrev_b32_e32 v3, 10, v12
	s_and_b64 s[42:43], s[34:35], s[26:27]
	v_lshlrev_b32_e32 v1, 4, v1
	v_or3_b32 v0, v1, v3, v0
	v_lshlrev_b32_e32 v0, 4, v0
	v_ashrrev_i32_e32 v1, 31, v0
	v_lshl_add_u64 v[0:1], v[0:1], 2, s[16:17]
	v_lshl_add_u64 v[0:1], v[0:1], 0, v[250:251]
	v_and_b32_e32 v16, 0x3ff, v7
	v_lshl_or_b32 v16, v12, 10, v16
	v_mad_u64_u32 v[244:245], s[26:27], v16, s2, v[8:9]
	v_mov_b64_e32 v[218:219], 0
	v_mov_b64_e32 v[220:221], 0
	v_mov_b64_e32 v[222:223], 0
	v_mov_b64_e32 v[224:225], 0
	s_mov_b64 exec, s[42:43]
	global_load_dwordx4 v[218:221], v[0:1], off
	global_load_dwordx4 v[222:225], v[0:1], off offset:16
	s_mov_b64 exec, s[22:23]
	v_lshl_add_u64 v[4:5], v[4:5], 0, s[4:5]
	v_cmp_ge_i64_e64 s[36:37], s[10:11], v[4:5]
	v_lshrrev_b32_e32 v7, 7, v4
	v_and_b32_e32 v0, 0x380, v7
	v_add_u32_e32 v0, 0x80, v0
	v_cmp_lt_u32_e64 s[26:27], v15, v0
	v_lshrrev_b32_e32 v12, 17, v4
	v_bfe_u32 v13, v7, 4, 6
	s_and_b64 s[36:37], s[36:37], s[26:27]
	v_cmp_ge_u32_e64 s[26:27], v13, v14
	v_sub_u32_e32 v1, v13, v14
	v_and_b32_e32 v0, 15, v7
	v_lshlrev_b32_e32 v3, 10, v12
	s_and_b64 s[44:45], s[36:37], s[26:27]
	v_lshlrev_b32_e32 v1, 4, v1
	v_or3_b32 v0, v1, v3, v0
	v_lshlrev_b32_e32 v0, 4, v0
	v_ashrrev_i32_e32 v1, 31, v0
	v_lshl_add_u64 v[0:1], v[0:1], 2, s[16:17]
	v_lshl_add_u64 v[0:1], v[0:1], 0, v[250:251]
	v_and_b32_e32 v16, 0x3ff, v7
	v_lshl_or_b32 v16, v12, 10, v16
	v_mad_u64_u32 v[246:247], s[26:27], v16, s2, v[8:9]
	v_mov_b64_e32 v[226:227], 0
	v_mov_b64_e32 v[228:229], 0
	v_mov_b64_e32 v[230:231], 0
	v_mov_b64_e32 v[232:233], 0
	s_mov_b64 exec, s[44:45]
	global_load_dwordx4 v[226:229], v[0:1], off
	global_load_dwordx4 v[230:233], v[0:1], off offset:16
	s_mov_b64 exec, s[22:23]
	v_lshl_add_u64 v[4:5], v[4:5], 0, s[4:5]
	v_cmp_ge_i64_e64 s[38:39], s[10:11], v[4:5]
	v_lshrrev_b32_e32 v7, 7, v4
	v_and_b32_e32 v0, 0x380, v7
	v_add_u32_e32 v0, 0x80, v0
	v_cmp_lt_u32_e64 s[26:27], v15, v0
	v_lshrrev_b32_e32 v12, 17, v4
	v_bfe_u32 v13, v7, 4, 6
	s_and_b64 s[38:39], s[38:39], s[26:27]
	v_cmp_ge_u32_e64 s[26:27], v13, v14
	v_sub_u32_e32 v1, v13, v14
	v_and_b32_e32 v0, 15, v7
	v_lshlrev_b32_e32 v3, 10, v12
	s_and_b64 s[46:47], s[38:39], s[26:27]
	v_lshlrev_b32_e32 v1, 4, v1
	v_or3_b32 v0, v1, v3, v0
	v_lshlrev_b32_e32 v0, 4, v0
	v_ashrrev_i32_e32 v1, 31, v0
	v_lshl_add_u64 v[0:1], v[0:1], 2, s[16:17]
	v_lshl_add_u64 v[0:1], v[0:1], 0, v[250:251]
	v_and_b32_e32 v16, 0x3ff, v7
	v_lshl_or_b32 v16, v12, 10, v16
	v_mad_u64_u32 v[248:249], s[26:27], v16, s2, v[8:9]
	v_mov_b64_e32 v[234:235], 0
	v_mov_b64_e32 v[236:237], 0
	v_mov_b64_e32 v[238:239], 0
	v_mov_b64_e32 v[240:241], 0
	s_mov_b64 exec, s[46:47]
	global_load_dwordx4 v[234:237], v[0:1], off
	global_load_dwordx4 v[238:241], v[0:1], off offset:16
	s_mov_b64 exec, s[22:23]
	v_lshl_add_u64 v[4:5], v[4:5], 0, s[4:5]
	s_waitcnt vmcnt(0)
	s_mov_b64 exec, s[32:33]
	v_cvt_pk_bf16_f32 v210, v210, v211
	v_cvt_pk_bf16_f32 v211, v212, v213
	v_cvt_pk_bf16_f32 v212, v214, v215
	v_cvt_pk_bf16_f32 v213, v216, v217
	global_store_dwordx4 v[242:243], v[210:213], off
	s_mov_b64 exec, s[34:35]
	v_cvt_pk_bf16_f32 v218, v218, v219
	v_cvt_pk_bf16_f32 v219, v220, v221
	v_cvt_pk_bf16_f32 v220, v222, v223
	v_cvt_pk_bf16_f32 v221, v224, v225
	global_store_dwordx4 v[244:245], v[218:221], off
	s_mov_b64 exec, s[36:37]
	v_cvt_pk_bf16_f32 v226, v226, v227
	v_cvt_pk_bf16_f32 v227, v228, v229
	v_cvt_pk_bf16_f32 v228, v230, v231
	v_cvt_pk_bf16_f32 v229, v232, v233
	global_store_dwordx4 v[246:247], v[226:229], off
	s_mov_b64 exec, s[38:39]
	v_cvt_pk_bf16_f32 v234, v234, v235
	v_cvt_pk_bf16_f32 v235, v236, v237
	v_cvt_pk_bf16_f32 v236, v238, v239
	v_cvt_pk_bf16_f32 v237, v240, v241
	global_store_dwordx4 v[248:249], v[234:237], off
	s_mov_b64 exec, s[22:23]
	v_cmp_ge_i64_e32 vcc, s[10:11], v[4:5]
	s_cbranch_vccnz .Lp3_toep_loop
